# speedup vs baseline: 1.0093x; 1.0093x over previous
; template <int BUFOFF>
; __device__ __forceinline__ void qkt_mla(f32x16& p0, f32x16& p1, const int* ka, const bf16x8* qr, const char* qlds) {
;   typedef __attribute__((address_space(3))) const bf16x8* lp;
;   p0 = f32x16{}; p1 = f32x16{};
; #pragma unroll
;   for (int d0 = 0; d0 < 12; ++d0) {
;     const int a = ka[d0 & 3] + (d0 >> 2) * 128 + BUFOFF;
;     const bf16x8 b0 = *(lp)(a), b1 = *(lp)(a + 12288);
;     bf16x8 qf;
;     qf = qr[d0];
;     p0 = __builtin_amdgcn_mfma_f32_32x32x16_bf16(b0, qf, p0, 0, 0, 0);
;     p1 = __builtin_amdgcn_mfma_f32_32x32x16_bf16(b1, qf, p1, 0, 0, 0);
;   }
; }
.LBB0_115:
	s_mov_b32 s55, s43
	s_mov_b32 s43, s52
	ds_read_b128 v[64:67], v169 offset:24576
	ds_read_b128 v[68:71], v169 offset:36864
	ds_read_b128 v[214:217], v190 offset:24576
	ds_read_b128 v[218:221], v190 offset:36864
	s_waitcnt lgkmcnt(0)
	v_mfma_f32_32x32x16_bf16 v[80:95], v[64:67], v[140:143], v[226:241]
	v_add_f32_e32 v144, v200, v145
	v_mfma_f32_32x32x16_bf16 v[64:79], v[68:71], v[140:143], v[226:241]
	v_add_f32_e32 v243, v203, v210
	v_add_f32_e32 v244, v202, v208
	v_add_f32_e32 v245, v205, v212
	v_add_f32_e32 v246, v199, v211
	v_add_f32_e32 v247, v201, v213
	v_mfma_f32_32x32x16_bf16 v[80:95], v[214:217], v[136:139], v[80:95]
	v_add_f32_e32 v251, v204, v207
	v_add_f32_e32 v252, v206, v209
	v_mov_b32_e32 v196, v158
	v_add_f32_e32 v144, v172, v144
	v_add_f32_e32 v243, v173, v243
	v_mfma_f32_32x32x16_bf16 v[64:79], v[218:221], v[136:139], v[64:79]
	ds_read_b128 v[214:217], v193 offset:24576
	ds_read_b128 v[218:221], v193 offset:36864
	v_add_f32_e32 v244, v170, v244
	v_add_f32_e32 v245, v171, v245
	v_add_f32_e32 v246, v196, v246
	v_mov_b32_e32 v222, v147
	v_mov_b32_e32 v223, v154
	v_mov_b32_e32 v224, v155
	s_waitcnt lgkmcnt(0)
	v_mfma_f32_32x32x16_bf16 v[80:95], v[214:217], v[132:135], v[80:95]
	v_mfma_f32_32x32x16_bf16 v[64:79], v[218:221], v[132:135], v[64:79]
	ds_read_b128 v[214:217], v192 offset:24576
	ds_read_b128 v[218:221], v192 offset:36864
	s_waitcnt lgkmcnt(0)
	v_mfma_f32_32x32x16_bf16 v[80:95], v[214:217], v[128:131], v[80:95]
	v_mfma_f32_32x32x16_bf16 v[64:79], v[218:221], v[128:131], v[64:79]
	ds_read_b128 v[214:217], v169 offset:24704
	ds_read_b128 v[218:221], v169 offset:36992
	s_waitcnt lgkmcnt(0)
	v_mfma_f32_32x32x16_bf16 v[80:95], v[214:217], v[124:127], v[80:95]
	v_mfma_f32_32x32x16_bf16 v[64:79], v[218:221], v[124:127], v[64:79]
	ds_read_b128 v[214:217], v190 offset:24704
	ds_read_b128 v[218:221], v190 offset:36992
	s_waitcnt lgkmcnt(0)
	v_mfma_f32_32x32x16_bf16 v[80:95], v[214:217], v[120:123], v[80:95]
	v_mfma_f32_32x32x16_bf16 v[64:79], v[218:221], v[120:123], v[64:79]
	ds_read_b128 v[214:217], v193 offset:24704
	ds_read_b128 v[218:221], v193 offset:36992
	s_waitcnt lgkmcnt(0)
	v_mfma_f32_32x32x16_bf16 v[80:95], v[214:217], v[116:119], v[80:95]
	v_mfma_f32_32x32x16_bf16 v[64:79], v[218:221], v[116:119], v[64:79]
	ds_read_b128 v[214:217], v192 offset:24704
	ds_read_b128 v[218:221], v192 offset:36992
	s_waitcnt lgkmcnt(0)
	v_mfma_f32_32x32x16_bf16 v[80:95], v[214:217], v[112:115], v[80:95]
	v_mfma_f32_32x32x16_bf16 v[64:79], v[218:221], v[112:115], v[64:79]
	ds_read_b128 v[214:217], v169 offset:24832
	ds_read_b128 v[218:221], v169 offset:37120
	s_waitcnt lgkmcnt(0)
	v_mfma_f32_32x32x16_bf16 v[80:95], v[214:217], v[108:111], v[80:95]
	v_mfma_f32_32x32x16_bf16 v[64:79], v[218:221], v[108:111], v[64:79]
	ds_read_b128 v[214:217], v190 offset:24832
	ds_read_b128 v[218:221], v190 offset:37120
	s_waitcnt lgkmcnt(0)
	v_mfma_f32_32x32x16_bf16 v[80:95], v[214:217], v[104:107], v[80:95]
	v_mfma_f32_32x32x16_bf16 v[64:79], v[218:221], v[104:107], v[64:79]
	ds_read_b128 v[214:217], v193 offset:24832
	ds_read_b128 v[218:221], v193 offset:37120
	s_waitcnt lgkmcnt(0)
	v_mfma_f32_32x32x16_bf16 v[80:95], v[214:217], v[100:103], v[80:95]
	v_mfma_f32_32x32x16_bf16 v[64:79], v[218:221], v[100:103], v[64:79]
	ds_read_b128 v[214:217], v192 offset:24832
	ds_read_b128 v[218:221], v192 offset:37120
	s_waitcnt lgkmcnt(0)
	v_mfma_f32_32x32x16_bf16 v[80:95], v[214:217], v[96:99], v[80:95]
	v_mov_b32_e32 v214, v159
	v_mov_b32_e32 v215, v152
	v_mov_b32_e32 v216, v153
	v_mov_b32_e32 v217, v150
	v_add_f32_e32 v247, v214, v247
	v_add_f32_e32 v251, v215, v251
	v_add_f32_e32 v252, v216, v252
	v_mfma_f32_32x32x16_bf16 v[64:79], v[218:221], v[96:99], v[64:79]
	v_mov_b32_e32 v218, v151
	v_mov_b32_e32 v219, v148
	v_mov_b32_e32 v220, v149
	v_mov_b32_e32 v221, v146
	v_add_f32_e32 v144, v217, v144
	v_add_f32_e32 v243, v218, v243
	v_add_f32_e32 v244, v219, v244
	v_add_f32_e32 v245, v220, v245
	v_add_f32_e32 v246, v221, v246
	v_add_f32_e32 v247, v222, v247
	v_add_f32_e32 v251, v223, v251
	v_add_f32_e32 v252, v224, v252
	v_add_f32_e32 v144, v144, v243
	v_add_f32_e32 v244, v244, v245
	v_add_f32_e32 v246, v246, v247
	v_add_f32_e32 v251, v251, v252
	v_add_f32_e32 v144, v144, v244
	v_add_f32_e32 v246, v246, v251
	v_add_f32_e32 v158, v144, v246
	v_mov_b32_e32 v159, v158
	v_cvt_pk_bf16_f32 v144, v145, v210
	v_cvt_pk_bf16_f32 v145, v208, v212
	v_cvt_pk_bf16_f32 v146, v211, v213
	v_cvt_pk_bf16_f32 v147, v207, v209
	v_cvt_pk_bf16_f32 v148, v200, v203
	v_cvt_pk_bf16_f32 v149, v202, v205
	v_cvt_pk_bf16_f32 v150, v199, v201
	v_cvt_pk_bf16_f32 v151, v204, v206
	v_cvt_pk_bf16_f32 v152, v172, v173
	v_cvt_pk_bf16_f32 v153, v170, v171
	v_cvt_pk_bf16_f32 v154, v196, v214
	s_nop 1
	v_permlane32_swap_b32_e32 v158, v159
	v_cvt_pk_bf16_f32 v155, v215, v216
	v_cvt_pk_bf16_f32 v170, v217, v218
	v_cvt_pk_bf16_f32 v171, v219, v220
	v_cvt_pk_bf16_f32 v172, v221, v222
	v_cvt_pk_bf16_f32 v173, v223, v224
	s_lshl_b32 s101, s43, 14
	v_add_u32_e32 v196, s101, v167
	ds_read_b64_tr_b16 v[200:201], v196 offset:0
	ds_read_b64_tr_b16 v[202:203], v196 offset:0x800
	ds_read_b64_tr_b16 v[204:205], v196 offset:0x1000
	ds_read_b64_tr_b16 v[206:207], v196 offset:0x1800
	ds_read_b64_tr_b16 v[208:209], v196 offset:0x2000
	ds_read_b64_tr_b16 v[210:211], v196 offset:0x2800
	ds_read_b64_tr_b16 v[212:213], v196 offset:0x3000
	ds_read_b64_tr_b16 v[214:215], v196 offset:0x3800
	v_readlane_b32 s58, v249, 37
	v_readlane_b32 s59, v249, 38
	s_add_u32 s56, s58, s47
	s_addc_u32 s57, s59, s50
	s_add_u32 s4, s56, 0x17060000
	s_addc_u32 s5, s57, 0
	s_add_u32 s58, s58, s14
	s_addc_u32 s59, s59, s15
	s_add_u32 s60, s58, 0x1a040000
	s_mov_b32 m0, s41
	s_addc_u32 s61, s59, 0
	s_lshl_b32 s52, s54, 14
	s_add_i32 s62, s40, s52
	global_load_lds_dwordx4 v188, s[4:5]
	s_mov_b32 m0, s42
	s_nop 0
	global_load_lds_dwordx4 v189, s[4:5]
	s_add_i32 m0, s41, 0x4000
	s_nop 0
	global_load_lds_dwordx4 v191, s[4:5]
	s_mov_b32 m0, s62
	s_nop 0
	global_load_lds_dwordx4 v194, s[60:61]
	s_add_i32 m0, s62, 0x2000
	s_nop 0
	global_load_lds_dwordx4 v195, s[60:61]
	s_lshl_b32 s60, s43, 14
	s_nop 0
	s_waitcnt lgkmcnt(6)
; #define SBAR() __builtin_amdgcn_sched_barrier(0)
; template <int MLA>
; __device__ __forceinline__ void partialSM(f32x16& p0, f32x16& p1, float& m_reg, float& mn, float& alpha) {
;     ...
;   float pmax = p0[0];
; #pragma unroll
;   for (int r = 1; r < 16; ++r) pmax = fmaxf(pmax, p0[r]);
; #pragma unroll
;   for (int r = 0; r < 16; ++r) pmax = fmaxf(pmax, p1[r]);
;   { auto rr = __builtin_amdgcn_permlane32_swap(__float_as_uint(pmax), __float_as_uint(pmax), false, false);
;     pmax = fmaxf(__uint_as_float(rr[0]), __uint_as_float(rr[1])); }
;   if (__builtin_expect(__all(pmax - m_reg <= THR / SCALE), 1)) { mn = m_reg; alpha = 1.f; }
;   else { mn = fmaxf(m_reg, pmax); alpha = __builtin_amdgcn_exp2f((m_reg - mn) * C); m_reg = mn; }
; template <int D0> __device__ __forceinline__ void pv_one_t(f32x16& od, int vb, bf16x8 pa0, bf16x8 pa1, bf16x8 pa2, bf16x8 pa3) {
;   const s16x4 l0 = tr_read<v_rd_off(D0, 0, 0)>(vb), h0 = tr_read<v_rd_off(D0, 0, 1)>(vb), l1 = tr_read<v_rd_off(D0, 1, 0)>(vb), h1 = tr_read<v_rd_off(D0, 1, 1)>(vb);
;   const s16x4 l2 = tr_read<v_rd_off(D0, 2, 0)>(vb), h2 = tr_read<v_rd_off(D0, 2, 1)>(vb), l3 = tr_read<v_rd_off(D0, 3, 0)>(vb), h3 = tr_read<v_rd_off(D0, 3, 1)>(vb);
;   asm volatile("s_waitcnt lgkmcnt(0)" ::: "memory"); SBAR();
;     ...
;   od = __builtin_amdgcn_mfma_f32_32x32x16_bf16(PK(l0, h0), pa0, od, 0, 0, 0);
;   od = __builtin_amdgcn_mfma_f32_32x32x16_bf16(PK(l1, h1), pa1, od, 0, 0, 0);
;   od = __builtin_amdgcn_mfma_f32_32x32x16_bf16(PK(l2, h2), pa2, od, 0, 0, 0);
;   od = __builtin_amdgcn_mfma_f32_32x32x16_bf16(PK(l3, h3), pa3, od, 0, 0, 0);
;     ...
; }
	v_mfma_f32_32x32x16_bf16 v[0:15], v[200:203], v[144:147], v[0:15]
	ds_read_b64_tr_b16 v[200:201], v196 offset:0x200
	ds_read_b64_tr_b16 v[202:203], v196 offset:0xa00
	s_waitcnt lgkmcnt(6)
	v_mfma_f32_32x32x16_bf16 v[0:15], v[204:207], v[148:151], v[0:15]
	ds_read_b64_tr_b16 v[204:205], v196 offset:0x1200
	ds_read_b64_tr_b16 v[206:207], v196 offset:0x1a00
	s_waitcnt lgkmcnt(6)
	v_mfma_f32_32x32x16_bf16 v[0:15], v[208:211], v[152:155], v[0:15]
	ds_read_b64_tr_b16 v[208:209], v196 offset:0x2200
	ds_read_b64_tr_b16 v[210:211], v196 offset:0x2a00
	s_waitcnt lgkmcnt(6)
	v_mfma_f32_32x32x16_bf16 v[0:15], v[212:215], v[170:173], v[0:15]
	ds_read_b64_tr_b16 v[212:213], v196 offset:0x3200
	ds_read_b64_tr_b16 v[214:215], v196 offset:0x3a00
	s_waitcnt lgkmcnt(6)
	v_mfma_f32_32x32x16_bf16 v[48:63], v[200:203], v[144:147], v[48:63]
	ds_read_b64_tr_b16 v[200:201], v196 offset:0x400
	ds_read_b64_tr_b16 v[202:203], v196 offset:0xc00
	s_waitcnt lgkmcnt(6)
	v_mfma_f32_32x32x16_bf16 v[48:63], v[204:207], v[148:151], v[48:63]
	ds_read_b64_tr_b16 v[204:205], v196 offset:0x1400
	ds_read_b64_tr_b16 v[206:207], v196 offset:0x1c00
	s_waitcnt lgkmcnt(6)
	v_mfma_f32_32x32x16_bf16 v[48:63], v[208:211], v[152:155], v[48:63]
	ds_read_b64_tr_b16 v[208:209], v196 offset:0x2400
	ds_read_b64_tr_b16 v[210:211], v196 offset:0x2c00
	s_waitcnt lgkmcnt(6)
	v_mfma_f32_32x32x16_bf16 v[48:63], v[212:215], v[170:173], v[48:63]
	ds_read_b64_tr_b16 v[212:213], v196 offset:0x3400
	ds_read_b64_tr_b16 v[214:215], v196 offset:0x3c00
	s_waitcnt lgkmcnt(6)
	v_mfma_f32_32x32x16_bf16 v[32:47], v[200:203], v[144:147], v[32:47]
	ds_read_b64_tr_b16 v[200:201], v196 offset:0x600
	ds_read_b64_tr_b16 v[202:203], v196 offset:0xe00
	s_waitcnt lgkmcnt(6)
	v_mfma_f32_32x32x16_bf16 v[32:47], v[204:207], v[148:151], v[32:47]
	ds_read_b64_tr_b16 v[204:205], v196 offset:0x1600
	ds_read_b64_tr_b16 v[206:207], v196 offset:0x1e00
	s_waitcnt lgkmcnt(6)
	v_mfma_f32_32x32x16_bf16 v[32:47], v[208:211], v[152:155], v[32:47]
	ds_read_b64_tr_b16 v[208:209], v196 offset:0x2600
	ds_read_b64_tr_b16 v[210:211], v196 offset:0x2e00
	s_waitcnt lgkmcnt(6)
	v_mfma_f32_32x32x16_bf16 v[32:47], v[212:215], v[170:173], v[32:47]
	ds_read_b64_tr_b16 v[212:213], v196 offset:0x3600
	ds_read_b64_tr_b16 v[214:215], v196 offset:0x3e00
	s_waitcnt lgkmcnt(6)
	v_mfma_f32_32x32x16_bf16 v[16:31], v[200:203], v[144:147], v[16:31]
	v_max_f32_e32 v144, v80, v81
	v_max3_f32 v144, v144, v82, v83
	v_max3_f32 v144, v144, v84, v85
	v_max3_f32 v144, v144, v86, v87
	v_max3_f32 v144, v144, v88, v89
	v_max3_f32 v144, v144, v90, v91
	v_max3_f32 v144, v144, v92, v93
	s_waitcnt lgkmcnt(4)
	v_mfma_f32_32x32x16_bf16 v[16:31], v[204:207], v[148:151], v[16:31]
	v_max3_f32 v144, v144, v94, v95
	v_max3_f32 v144, v144, v64, v65
	v_max3_f32 v144, v144, v66, v67
	v_max3_f32 v144, v144, v68, v69
	v_max3_f32 v144, v144, v70, v71
	v_max3_f32 v144, v144, v72, v73
	v_max3_f32 v144, v144, v74, v75
	v_max3_f32 v144, v144, v76, v77
	s_waitcnt lgkmcnt(2)
	v_mfma_f32_32x32x16_bf16 v[16:31], v[208:211], v[152:155], v[16:31]
	v_max3_f32 v144, v144, v78, v79
	v_mov_b32_e32 v145, v144
	s_nop 1
	v_permlane32_swap_b32_e32 v144, v145
	v_max_f32_e32 v144, v144, v145
	v_cmp_ge_f32_e32 vcc, s63, v144
	s_waitcnt lgkmcnt(0)
	v_mfma_f32_32x32x16_bf16 v[16:31], v[212:215], v[170:173], v[16:31]
	s_cmp_eq_u64 vcc, exec
	s_cselect_b64 s[4:5], -1, 0
	s_waitcnt vmcnt(0) lgkmcnt(0)
	s_barrier
	s_cbranch_scc1 .Lal_c_m1
	v_max_f32_e32 v242, 0, v144
	v_exp_f32_e64 v152, -v242
	s_nop 0
	v_pk_mul_f32 v[14:15], v[14:15], v[152:153] op_sel_hi:[1,0]
	v_pk_mul_f32 v[12:13], v[12:13], v[152:153] op_sel_hi:[1,0]
	v_pk_mul_f32 v[10:11], v[10:11], v[152:153] op_sel_hi:[1,0]
	v_pk_mul_f32 v[8:9], v[8:9], v[152:153] op_sel_hi:[1,0]
	v_pk_mul_f32 v[6:7], v[6:7], v[152:153] op_sel_hi:[1,0]
	v_pk_mul_f32 v[4:5], v[4:5], v[152:153] op_sel_hi:[1,0]
	v_pk_mul_f32 v[2:3], v[2:3], v[152:153] op_sel_hi:[1,0]
	v_pk_mul_f32 v[0:1], v[0:1], v[152:153] op_sel_hi:[1,0]
	v_pk_mul_f32 v[62:63], v[62:63], v[152:153] op_sel_hi:[1,0]
	v_pk_mul_f32 v[60:61], v[60:61], v[152:153] op_sel_hi:[1,0]
	v_pk_mul_f32 v[58:59], v[58:59], v[152:153] op_sel_hi:[1,0]
	v_pk_mul_f32 v[56:57], v[56:57], v[152:153] op_sel_hi:[1,0]
	v_pk_mul_f32 v[54:55], v[54:55], v[152:153] op_sel_hi:[1,0]
	v_pk_mul_f32 v[52:53], v[52:53], v[152:153] op_sel_hi:[1,0]
	v_pk_mul_f32 v[50:51], v[50:51], v[152:153] op_sel_hi:[1,0]
	v_pk_mul_f32 v[48:49], v[48:49], v[152:153] op_sel_hi:[1,0]
	v_pk_mul_f32 v[46:47], v[46:47], v[152:153] op_sel_hi:[1,0]
	v_pk_mul_f32 v[44:45], v[44:45], v[152:153] op_sel_hi:[1,0]
	v_pk_mul_f32 v[42:43], v[42:43], v[152:153] op_sel_hi:[1,0]
	v_pk_mul_f32 v[40:41], v[40:41], v[152:153] op_sel_hi:[1,0]
	v_pk_mul_f32 v[38:39], v[38:39], v[152:153] op_sel_hi:[1,0]
	v_pk_mul_f32 v[36:37], v[36:37], v[152:153] op_sel_hi:[1,0]
	v_pk_mul_f32 v[34:35], v[34:35], v[152:153] op_sel_hi:[1,0]
	v_pk_mul_f32 v[32:33], v[32:33], v[152:153] op_sel_hi:[1,0]
	v_pk_mul_f32 v[30:31], v[30:31], v[152:153] op_sel_hi:[1,0]
	v_pk_mul_f32 v[28:29], v[28:29], v[152:153] op_sel_hi:[1,0]
	v_pk_mul_f32 v[26:27], v[26:27], v[152:153] op_sel_hi:[1,0]
	v_pk_mul_f32 v[24:25], v[24:25], v[152:153] op_sel_hi:[1,0]
	v_pk_mul_f32 v[22:23], v[22:23], v[152:153] op_sel_hi:[1,0]
	v_pk_mul_f32 v[20:21], v[20:21], v[152:153] op_sel_hi:[1,0]
	v_pk_mul_f32 v[18:19], v[18:19], v[152:153] op_sel_hi:[1,0]
	v_pk_mul_f32 v[16:17], v[16:17], v[152:153] op_sel_hi:[1,0]
	v_sub_f32_e32 v80, v80, v242
	v_sub_f32_e32 v81, v81, v242
	v_sub_f32_e32 v82, v82, v242
	v_sub_f32_e32 v83, v83, v242
	v_sub_f32_e32 v84, v84, v242
	v_sub_f32_e32 v85, v85, v242
	v_sub_f32_e32 v86, v86, v242
	v_sub_f32_e32 v87, v87, v242
	v_sub_f32_e32 v88, v88, v242
	v_sub_f32_e32 v89, v89, v242
	v_sub_f32_e32 v90, v90, v242
	v_sub_f32_e32 v91, v91, v242
	v_sub_f32_e32 v92, v92, v242
	v_sub_f32_e32 v93, v93, v242
	v_sub_f32_e32 v94, v94, v242
	v_sub_f32_e32 v95, v95, v242
	v_sub_f32_e32 v64, v64, v242
	v_sub_f32_e32 v65, v65, v242
	v_sub_f32_e32 v66, v66, v242
	v_sub_f32_e32 v67, v67, v242
	v_sub_f32_e32 v68, v68, v242
	v_sub_f32_e32 v69, v69, v242
	v_sub_f32_e32 v70, v70, v242
	v_sub_f32_e32 v71, v71, v242
	v_sub_f32_e32 v72, v72, v242
	v_sub_f32_e32 v73, v73, v242
	v_sub_f32_e32 v74, v74, v242
	v_sub_f32_e32 v75, v75, v242
	v_sub_f32_e32 v76, v76, v242
	v_sub_f32_e32 v77, v77, v242
	v_sub_f32_e32 v78, v78, v242
	v_sub_f32_e32 v79, v79, v242
	v_sub_f32_e32 v226, v226, v242
	v_sub_f32_e32 v227, v227, v242
	v_sub_f32_e32 v228, v228, v242
	v_sub_f32_e32 v229, v229, v242
	v_sub_f32_e32 v230, v230, v242
	v_sub_f32_e32 v231, v231, v242
	v_sub_f32_e32 v232, v232, v242
	v_sub_f32_e32 v233, v233, v242
	v_sub_f32_e32 v234, v234, v242
	v_sub_f32_e32 v235, v235, v242
	v_sub_f32_e32 v236, v236, v242
	v_sub_f32_e32 v237, v237, v242
	v_sub_f32_e32 v238, v238, v242
	v_sub_f32_e32 v239, v239, v242
	v_sub_f32_e32 v240, v240, v242
	v_sub_f32_e32 v241, v241, v242
	s_branch .LBB0_117

; __device__ __forceinline__ void finishSM(f32x16& p0, f32x16& p1, float alpha, float& l_reg, bf16x8& pa0, bf16x8& pa1, bf16x8& pa2, bf16x8& pa3) {
; #pragma unroll
;   for (int r = 0; r < 16; ++r) p1[r] = __builtin_amdgcn_exp2f(p1[r]);
;   float ps = 0;
; #pragma unroll
;   for (int r = 0; r < 16; ++r) ps += p0[r];
; #pragma unroll
;   for (int r = 0; r < 16; ++r) ps += p1[r];
;   { auto rr = __builtin_amdgcn_permlane32_swap(__float_as_uint(ps), __float_as_uint(ps), false, false);
;     ps = __uint_as_float(rr[0]) + __uint_as_float(rr[1]); }
;   l_reg = l_reg * alpha + ps;
;     ...
;   PK4(p0, 0, pa0); PK4(p0, 8, pa1); PK4(p1, 0, pa2); PK4(p1, 8, pa3);
;     ...
; }
; template <int BUFOFF>
; __device__ __forceinline__ void qkt_mla(f32x16& p0, f32x16& p1, const int* ka, const bf16x8* qr, const char* qlds) {
;   typedef __attribute__((address_space(3))) const bf16x8* lp;
;   p0 = f32x16{}; p1 = f32x16{};
; #pragma unroll
;   for (int d0 = 0; d0 < 12; ++d0) {
;     const int a = ka[d0 & 3] + (d0 >> 2) * 128 + BUFOFF;
;     const bf16x8 b0 = *(lp)(a), b1 = *(lp)(a + 12288);
;     bf16x8 qf;
;     qf = qr[d0];
;     p0 = __builtin_amdgcn_mfma_f32_32x32x16_bf16(b0, qf, p0, 0, 0, 0);
;     p1 = __builtin_amdgcn_mfma_f32_32x32x16_bf16(b1, qf, p1, 0, 0, 0);
;   }
; }
.LBB0_117:
	v_exp_f32_e32 v155, v64
	v_exp_f32_e32 v170, v65
	v_exp_f32_e32 v171, v66
	v_exp_f32_e32 v172, v67
	v_exp_f32_e32 v173, v68
	v_exp_f32_e32 v197, v69
	v_exp_f32_e32 v199, v70
	v_exp_f32_e32 v200, v71
	v_exp_f32_e32 v201, v72
	v_exp_f32_e32 v202, v73
	v_exp_f32_e32 v203, v74
	v_exp_f32_e32 v204, v75
	v_exp_f32_e32 v205, v76
	v_exp_f32_e32 v222, v77
	v_exp_f32_e32 v223, v78
	v_exp_f32_e32 v154, v79
	v_exp_f32_e32 v206, v80
	v_exp_f32_e32 v207, v81
	v_exp_f32_e32 v208, v82
	v_exp_f32_e32 v209, v83
	v_exp_f32_e32 v210, v84
	v_exp_f32_e32 v211, v85
	v_exp_f32_e32 v212, v86
	v_exp_f32_e32 v213, v87
	v_exp_f32_e32 v214, v88
	v_exp_f32_e32 v215, v89
	v_exp_f32_e32 v216, v90
	v_exp_f32_e32 v217, v91
	v_exp_f32_e32 v218, v92
	v_exp_f32_e32 v219, v93
	v_exp_f32_e32 v220, v94
	v_exp_f32_e32 v221, v95
	ds_read_b128 v[64:67], v169
	ds_read_b128 v[68:71], v169 offset:12288
	ds_read_b128 v[144:147], v190
	ds_read_b128 v[148:151], v190 offset:12288
	v_mov_b32_e32 v224, v155
	s_waitcnt lgkmcnt(0)
	v_mfma_f32_32x32x16_bf16 v[80:95], v[64:67], v[140:143], v[226:241]
	v_mfma_f32_32x32x16_bf16 v[64:79], v[68:71], v[140:143], v[226:241]
	v_mov_b32_e32 v225, v154
	v_mfma_f32_32x32x16_bf16 v[80:95], v[144:147], v[136:139], v[80:95]
	v_mfma_f32_32x32x16_bf16 v[64:79], v[148:151], v[136:139], v[64:79]
	ds_read_b128 v[144:147], v193
	ds_read_b128 v[148:151], v193 offset:12288
	s_waitcnt lgkmcnt(0)
	v_mfma_f32_32x32x16_bf16 v[80:95], v[144:147], v[132:135], v[80:95]
	v_mfma_f32_32x32x16_bf16 v[64:79], v[148:151], v[132:135], v[64:79]
	ds_read_b128 v[144:147], v192
	ds_read_b128 v[148:151], v192 offset:12288
	s_waitcnt lgkmcnt(0)
	v_mfma_f32_32x32x16_bf16 v[80:95], v[144:147], v[128:131], v[80:95]
	v_mfma_f32_32x32x16_bf16 v[64:79], v[148:151], v[128:131], v[64:79]
	ds_read_b128 v[144:147], v169 offset:128
	ds_read_b128 v[148:151], v169 offset:12416
	s_waitcnt lgkmcnt(0)
	v_mfma_f32_32x32x16_bf16 v[80:95], v[144:147], v[124:127], v[80:95]
	v_mfma_f32_32x32x16_bf16 v[64:79], v[148:151], v[124:127], v[64:79]
	ds_read_b128 v[144:147], v190 offset:128
	ds_read_b128 v[148:151], v190 offset:12416
	s_waitcnt lgkmcnt(0)
	v_mfma_f32_32x32x16_bf16 v[80:95], v[144:147], v[120:123], v[80:95]
	v_mfma_f32_32x32x16_bf16 v[64:79], v[148:151], v[120:123], v[64:79]
	ds_read_b128 v[144:147], v193 offset:128
	ds_read_b128 v[148:151], v193 offset:12416
	s_waitcnt lgkmcnt(0)
	v_mfma_f32_32x32x16_bf16 v[80:95], v[144:147], v[116:119], v[80:95]
	v_mfma_f32_32x32x16_bf16 v[64:79], v[148:151], v[116:119], v[64:79]
	ds_read_b128 v[144:147], v192 offset:128
	ds_read_b128 v[148:151], v192 offset:12416
	s_waitcnt lgkmcnt(0)
	v_mfma_f32_32x32x16_bf16 v[80:95], v[144:147], v[112:115], v[80:95]
	v_mfma_f32_32x32x16_bf16 v[64:79], v[148:151], v[112:115], v[64:79]
	ds_read_b128 v[144:147], v169 offset:256
	ds_read_b128 v[148:151], v169 offset:12544
	s_waitcnt lgkmcnt(0)
	v_mfma_f32_32x32x16_bf16 v[80:95], v[144:147], v[108:111], v[80:95]
	v_mfma_f32_32x32x16_bf16 v[64:79], v[148:151], v[108:111], v[64:79]
	ds_read_b128 v[144:147], v190 offset:256
	ds_read_b128 v[148:151], v190 offset:12544
	s_waitcnt lgkmcnt(0)
	v_mfma_f32_32x32x16_bf16 v[80:95], v[144:147], v[104:107], v[80:95]
	v_mfma_f32_32x32x16_bf16 v[64:79], v[148:151], v[104:107], v[64:79]
	ds_read_b128 v[144:147], v193 offset:256
	ds_read_b128 v[148:151], v193 offset:12544
	s_waitcnt lgkmcnt(0)
	v_mfma_f32_32x32x16_bf16 v[80:95], v[144:147], v[100:103], v[80:95]
	v_mfma_f32_32x32x16_bf16 v[64:79], v[148:151], v[100:103], v[64:79]
	ds_read_b128 v[144:147], v192 offset:256
	ds_read_b128 v[148:151], v192 offset:12544
	s_waitcnt lgkmcnt(0)
	v_mfma_f32_32x32x16_bf16 v[80:95], v[144:147], v[96:99], v[80:95]
	v_add_f32_e32 v144, v214, v206
	v_add_f32_e32 v243, v215, v207
	v_add_f32_e32 v244, v216, v208
	v_add_f32_e32 v245, v217, v209
	v_add_f32_e32 v246, v218, v210
	v_add_f32_e32 v247, v219, v211
	v_add_f32_e32 v251, v220, v212
	v_add_f32_e32 v252, v221, v213
	v_add_f32_e32 v144, v224, v144
	v_add_f32_e32 v243, v170, v243
	v_add_f32_e32 v244, v171, v244
	v_add_f32_e32 v245, v172, v245
	v_add_f32_e32 v246, v173, v246
	v_add_f32_e32 v247, v197, v247
	v_add_f32_e32 v251, v199, v251
	v_add_f32_e32 v252, v200, v252
	v_add_f32_e32 v144, v201, v144
	v_add_f32_e32 v243, v202, v243
	v_mfma_f32_32x32x16_bf16 v[64:79], v[148:151], v[96:99], v[64:79]
	v_add_f32_e32 v244, v203, v244
	v_add_f32_e32 v245, v204, v245
	v_add_f32_e32 v246, v205, v246
	v_add_f32_e32 v247, v222, v247
	v_add_f32_e32 v251, v223, v251
	v_add_f32_e32 v252, v225, v252
	v_add_f32_e32 v144, v144, v243
	v_add_f32_e32 v244, v244, v245
	v_add_f32_e32 v246, v246, v247
	v_add_f32_e32 v251, v251, v252
	v_add_f32_e32 v144, v144, v244
	v_add_f32_e32 v246, v246, v251
	v_add_f32_e32 v154, v144, v246
	v_mov_b32_e32 v155, v154
	v_cvt_pk_bf16_f32 v144, v206, v207
	v_cvt_pk_bf16_f32 v145, v208, v209
	v_cvt_pk_bf16_f32 v146, v210, v211
	v_cvt_pk_bf16_f32 v147, v212, v213
	s_nop 1
	v_permlane32_swap_b32_e32 v154, v155
	v_cvt_pk_bf16_f32 v148, v214, v215
	v_cvt_pk_bf16_f32 v149, v216, v217
	v_cvt_pk_bf16_f32 v150, v218, v219
	v_cvt_pk_bf16_f32 v151, v220, v221
	v_cvt_pk_bf16_f32 v170, v224, v170
	v_cvt_pk_bf16_f32 v171, v171, v172
	v_cvt_pk_bf16_f32 v172, v173, v197
	v_cvt_pk_bf16_f32 v173, v199, v200
	v_cvt_pk_bf16_f32 v200, v201, v202
	v_cvt_pk_bf16_f32 v201, v203, v204
	v_cvt_pk_bf16_f32 v202, v205, v222
	v_cvt_pk_bf16_f32 v203, v223, v225
	v_lshl_add_u32 v197, s55, 14, v167
	ds_read_b64_tr_b16 v[204:205], v197 offset:0
	ds_read_b64_tr_b16 v[206:207], v197 offset:0x800
	ds_read_b64_tr_b16 v[208:209], v197 offset:0x1000
	ds_read_b64_tr_b16 v[210:211], v197 offset:0x1800
	ds_read_b64_tr_b16 v[212:213], v197 offset:0x2000
	ds_read_b64_tr_b16 v[214:215], v197 offset:0x2800
	ds_read_b64_tr_b16 v[216:217], v197 offset:0x3000
	ds_read_b64_tr_b16 v[218:219], v197 offset:0x3800
	s_nop 0
	s_add_u32 s4, s56, 0x17090000
	s_addc_u32 s5, s57, 0
	s_add_u32 s56, s58, 0x1a060000
	s_mov_b32 m0, s16
	s_addc_u32 s57, s59, 0
	s_add_i32 s58, s40, s60
	global_load_lds_dwordx4 v188, s[4:5]
	s_mov_b32 m0, s17
	s_nop 0
	global_load_lds_dwordx4 v189, s[4:5]
	s_mov_b32 m0, s44
	s_nop 0
	global_load_lds_dwordx4 v191, s[4:5]
	s_mov_b32 m0, s58
	s_nop 0
	global_load_lds_dwordx4 v194, s[56:57]
	s_add_i32 m0, s58, 0x2000
	s_nop 0
	global_load_lds_dwordx4 v195, s[56:57]
	s_nop 0
	s_waitcnt lgkmcnt(6)
; #define SBAR() __builtin_amdgcn_sched_barrier(0)
; template <int MLA>
; __device__ __forceinline__ void partialSM(f32x16& p0, f32x16& p1, float& m_reg, float& mn, float& alpha) {
;   constexpr float SCALE = AttC<MLA>::SCALE;
;   constexpr float C = SCALE * 1.4426950408889634f;
;   float pmax = p0[0];
; #pragma unroll
;   for (int r = 1; r < 16; ++r) pmax = fmaxf(pmax, p0[r]);
; #pragma unroll
;   for (int r = 0; r < 16; ++r) pmax = fmaxf(pmax, p1[r]);
;   { auto rr = __builtin_amdgcn_permlane32_swap(__float_as_uint(pmax), __float_as_uint(pmax), false, false);
;     pmax = fmaxf(__uint_as_float(rr[0]), __uint_as_float(rr[1])); }
;   if (__builtin_expect(__all(pmax - m_reg <= THR / SCALE), 1)) { mn = m_reg; alpha = 1.f; }
;   else { mn = fmaxf(m_reg, pmax); alpha = __builtin_amdgcn_exp2f((m_reg - mn) * C); m_reg = mn; }
;   float mnC = -mn * C;
; #pragma unroll
;   for (int r = 0; r < 16; ++r) p0[r] = fmaf(p0[r], C, mnC);
; #pragma unroll
;   for (int r = 0; r < 16; ++r) p1[r] = fmaf(p1[r], C, mnC);
; #pragma unroll
;   for (int r = 0; r < 16; ++r) p0[r] = __builtin_amdgcn_exp2f(p0[r]);
; }
; template <int D0> __device__ __forceinline__ void pv_one_t(f32x16& od, int vb, bf16x8 pa0, bf16x8 pa1, bf16x8 pa2, bf16x8 pa3) {
;   const s16x4 l0 = tr_read<v_rd_off(D0, 0, 0)>(vb), h0 = tr_read<v_rd_off(D0, 0, 1)>(vb), l1 = tr_read<v_rd_off(D0, 1, 0)>(vb), h1 = tr_read<v_rd_off(D0, 1, 1)>(vb);
;   const s16x4 l2 = tr_read<v_rd_off(D0, 2, 0)>(vb), h2 = tr_read<v_rd_off(D0, 2, 1)>(vb), l3 = tr_read<v_rd_off(D0, 3, 0)>(vb), h3 = tr_read<v_rd_off(D0, 3, 1)>(vb);
;   asm volatile("s_waitcnt lgkmcnt(0)" ::: "memory"); SBAR();
;     ...
;   od = __builtin_amdgcn_mfma_f32_32x32x16_bf16(PK(l0, h0), pa0, od, 0, 0, 0);
;   od = __builtin_amdgcn_mfma_f32_32x32x16_bf16(PK(l1, h1), pa1, od, 0, 0, 0);
;   od = __builtin_amdgcn_mfma_f32_32x32x16_bf16(PK(l2, h2), pa2, od, 0, 0, 0);
;   od = __builtin_amdgcn_mfma_f32_32x32x16_bf16(PK(l3, h3), pa3, od, 0, 0, 0);
;     ...
; }
; __device__ __forceinline__ void pv_d0_t(f32x16* o, int vb, bf16x8 pa0, bf16x8 pa1, bf16x8 pa2, bf16x8 pa3) {
;   pv_one_t<0>(o[0], vb, pa0, pa1, pa2, pa3); pv_one_t<1>(o[1], vb, pa0, pa1, pa2, pa3); pv_one_t<2>(o[2], vb, pa0, pa1, pa2, pa3); pv_one_t<3>(o[3], vb, pa0, pa1, pa2, pa3);
; }
	v_mfma_f32_32x32x16_bf16 v[0:15], v[204:207], v[144:147], v[0:15]
	ds_read_b64_tr_b16 v[204:205], v197 offset:0x200
	ds_read_b64_tr_b16 v[206:207], v197 offset:0xa00
	s_waitcnt lgkmcnt(6)
	v_mfma_f32_32x32x16_bf16 v[0:15], v[208:211], v[148:151], v[0:15]
	ds_read_b64_tr_b16 v[208:209], v197 offset:0x1200
	ds_read_b64_tr_b16 v[210:211], v197 offset:0x1a00
	s_waitcnt lgkmcnt(6)
	v_mfma_f32_32x32x16_bf16 v[0:15], v[212:215], v[170:173], v[0:15]
	ds_read_b64_tr_b16 v[212:213], v197 offset:0x2200
	ds_read_b64_tr_b16 v[214:215], v197 offset:0x2a00
	s_waitcnt lgkmcnt(6)
	v_mfma_f32_32x32x16_bf16 v[0:15], v[216:219], v[200:203], v[0:15]
	ds_read_b64_tr_b16 v[216:217], v197 offset:0x3200
	ds_read_b64_tr_b16 v[218:219], v197 offset:0x3a00
	s_waitcnt lgkmcnt(6)
	v_mfma_f32_32x32x16_bf16 v[48:63], v[204:207], v[144:147], v[48:63]
	ds_read_b64_tr_b16 v[204:205], v197 offset:0x400
	ds_read_b64_tr_b16 v[206:207], v197 offset:0xc00
	s_waitcnt lgkmcnt(6)
	v_mfma_f32_32x32x16_bf16 v[48:63], v[208:211], v[148:151], v[48:63]
	ds_read_b64_tr_b16 v[208:209], v197 offset:0x1400
	ds_read_b64_tr_b16 v[210:211], v197 offset:0x1c00
	s_waitcnt lgkmcnt(6)
	v_mfma_f32_32x32x16_bf16 v[48:63], v[212:215], v[170:173], v[48:63]
	ds_read_b64_tr_b16 v[212:213], v197 offset:0x2400
	ds_read_b64_tr_b16 v[214:215], v197 offset:0x2c00
	s_waitcnt lgkmcnt(6)
	v_mfma_f32_32x32x16_bf16 v[48:63], v[216:219], v[200:203], v[48:63]
	ds_read_b64_tr_b16 v[216:217], v197 offset:0x3400
	ds_read_b64_tr_b16 v[218:219], v197 offset:0x3c00
	s_waitcnt lgkmcnt(6)
	v_mfma_f32_32x32x16_bf16 v[32:47], v[204:207], v[144:147], v[32:47]
	ds_read_b64_tr_b16 v[204:205], v197 offset:0x600
	ds_read_b64_tr_b16 v[206:207], v197 offset:0xe00
	s_waitcnt lgkmcnt(6)
	v_mfma_f32_32x32x16_bf16 v[32:47], v[208:211], v[148:151], v[32:47]
	ds_read_b64_tr_b16 v[208:209], v197 offset:0x1600
	ds_read_b64_tr_b16 v[210:211], v197 offset:0x1e00
	s_waitcnt lgkmcnt(6)
	v_mfma_f32_32x32x16_bf16 v[32:47], v[212:215], v[170:173], v[32:47]
	ds_read_b64_tr_b16 v[212:213], v197 offset:0x2600
	ds_read_b64_tr_b16 v[214:215], v197 offset:0x2e00
	s_waitcnt lgkmcnt(6)
	v_mfma_f32_32x32x16_bf16 v[32:47], v[216:219], v[200:203], v[32:47]
	ds_read_b64_tr_b16 v[216:217], v197 offset:0x3600
	ds_read_b64_tr_b16 v[218:219], v197 offset:0x3e00
	s_waitcnt lgkmcnt(6)
	v_mfma_f32_32x32x16_bf16 v[16:31], v[204:207], v[144:147], v[16:31]
	v_max_f32_e32 v144, v80, v81
	v_max3_f32 v144, v144, v82, v83
	v_max3_f32 v144, v144, v84, v85
	v_max3_f32 v144, v144, v86, v87
	v_max3_f32 v144, v144, v88, v89
	v_max3_f32 v144, v144, v90, v91
	v_max3_f32 v144, v144, v92, v93
	s_waitcnt lgkmcnt(4)
	v_mfma_f32_32x32x16_bf16 v[16:31], v[208:211], v[148:151], v[16:31]
	v_max3_f32 v144, v144, v94, v95
	v_max3_f32 v144, v144, v64, v65
	v_max3_f32 v144, v144, v66, v67
	v_max3_f32 v144, v144, v68, v69
	v_max3_f32 v144, v144, v70, v71
	v_max3_f32 v144, v144, v72, v73
	v_max3_f32 v144, v144, v74, v75
	v_max3_f32 v144, v144, v76, v77
	s_waitcnt lgkmcnt(2)
	v_mfma_f32_32x32x16_bf16 v[16:31], v[212:215], v[170:173], v[16:31]
	v_max3_f32 v144, v144, v78, v79
	v_mov_b32_e32 v145, v144
	s_nop 1
	v_permlane32_swap_b32_e32 v144, v145
	v_max_f32_e32 v144, v144, v145
	v_cmp_ge_f32_e32 vcc, s63, v144
	s_waitcnt lgkmcnt(0)
	v_mfma_f32_32x32x16_bf16 v[16:31], v[216:219], v[200:203], v[16:31]
	s_cmp_eq_u64 vcc, exec
	s_cselect_b64 s[4:5], -1, 0
	s_waitcnt vmcnt(0) lgkmcnt(0)
	s_barrier
	s_cbranch_scc1 .Lal_c_m2
	v_max_f32_e32 v242, 0, v144
	v_exp_f32_e64 v144, -v242
	s_nop 0
	v_pk_mul_f32 v[14:15], v[14:15], v[144:145] op_sel_hi:[1,0]
	v_pk_mul_f32 v[12:13], v[12:13], v[144:145] op_sel_hi:[1,0]
	v_pk_mul_f32 v[10:11], v[10:11], v[144:145] op_sel_hi:[1,0]
	v_pk_mul_f32 v[8:9], v[8:9], v[144:145] op_sel_hi:[1,0]
	v_pk_mul_f32 v[6:7], v[6:7], v[144:145] op_sel_hi:[1,0]
	v_pk_mul_f32 v[4:5], v[4:5], v[144:145] op_sel_hi:[1,0]
	v_pk_mul_f32 v[2:3], v[2:3], v[144:145] op_sel_hi:[1,0]
	v_pk_mul_f32 v[0:1], v[0:1], v[144:145] op_sel_hi:[1,0]
	v_pk_mul_f32 v[62:63], v[62:63], v[144:145] op_sel_hi:[1,0]
	v_pk_mul_f32 v[60:61], v[60:61], v[144:145] op_sel_hi:[1,0]
	v_pk_mul_f32 v[58:59], v[58:59], v[144:145] op_sel_hi:[1,0]
	v_pk_mul_f32 v[56:57], v[56:57], v[144:145] op_sel_hi:[1,0]
	v_pk_mul_f32 v[54:55], v[54:55], v[144:145] op_sel_hi:[1,0]
	v_pk_mul_f32 v[52:53], v[52:53], v[144:145] op_sel_hi:[1,0]
	v_pk_mul_f32 v[50:51], v[50:51], v[144:145] op_sel_hi:[1,0]
	v_pk_mul_f32 v[48:49], v[48:49], v[144:145] op_sel_hi:[1,0]
	v_pk_mul_f32 v[46:47], v[46:47], v[144:145] op_sel_hi:[1,0]
	v_pk_mul_f32 v[44:45], v[44:45], v[144:145] op_sel_hi:[1,0]
	v_pk_mul_f32 v[42:43], v[42:43], v[144:145] op_sel_hi:[1,0]
	v_pk_mul_f32 v[40:41], v[40:41], v[144:145] op_sel_hi:[1,0]
	v_pk_mul_f32 v[38:39], v[38:39], v[144:145] op_sel_hi:[1,0]
	v_pk_mul_f32 v[36:37], v[36:37], v[144:145] op_sel_hi:[1,0]
	v_pk_mul_f32 v[34:35], v[34:35], v[144:145] op_sel_hi:[1,0]
	v_pk_mul_f32 v[32:33], v[32:33], v[144:145] op_sel_hi:[1,0]
	v_pk_mul_f32 v[30:31], v[30:31], v[144:145] op_sel_hi:[1,0]
	v_pk_mul_f32 v[28:29], v[28:29], v[144:145] op_sel_hi:[1,0]
	v_pk_mul_f32 v[26:27], v[26:27], v[144:145] op_sel_hi:[1,0]
	v_pk_mul_f32 v[24:25], v[24:25], v[144:145] op_sel_hi:[1,0]
	v_pk_mul_f32 v[22:23], v[22:23], v[144:145] op_sel_hi:[1,0]
	v_pk_mul_f32 v[20:21], v[20:21], v[144:145] op_sel_hi:[1,0]
	v_pk_mul_f32 v[18:19], v[18:19], v[144:145] op_sel_hi:[1,0]
	v_pk_mul_f32 v[16:17], v[16:17], v[144:145] op_sel_hi:[1,0]
	v_sub_f32_e32 v80, v80, v242
	v_sub_f32_e32 v81, v81, v242
	v_sub_f32_e32 v82, v82, v242
	v_sub_f32_e32 v83, v83, v242
	v_sub_f32_e32 v84, v84, v242
	v_sub_f32_e32 v85, v85, v242
	v_sub_f32_e32 v86, v86, v242
	v_sub_f32_e32 v87, v87, v242
	v_sub_f32_e32 v88, v88, v242
	v_sub_f32_e32 v89, v89, v242
	v_sub_f32_e32 v90, v90, v242
	v_sub_f32_e32 v91, v91, v242
	v_sub_f32_e32 v92, v92, v242
	v_sub_f32_e32 v93, v93, v242
	v_sub_f32_e32 v94, v94, v242
	v_sub_f32_e32 v95, v95, v242
	v_sub_f32_e32 v64, v64, v242
	v_sub_f32_e32 v65, v65, v242
	v_sub_f32_e32 v66, v66, v242
	v_sub_f32_e32 v67, v67, v242
	v_sub_f32_e32 v68, v68, v242
	v_sub_f32_e32 v69, v69, v242
	v_sub_f32_e32 v70, v70, v242
	v_sub_f32_e32 v71, v71, v242
	v_sub_f32_e32 v72, v72, v242
	v_sub_f32_e32 v73, v73, v242
	v_sub_f32_e32 v74, v74, v242
	v_sub_f32_e32 v75, v75, v242
	v_sub_f32_e32 v76, v76, v242
	v_sub_f32_e32 v77, v77, v242
	v_sub_f32_e32 v78, v78, v242
	v_sub_f32_e32 v79, v79, v242
	v_sub_f32_e32 v226, v226, v242
	v_sub_f32_e32 v227, v227, v242
	v_sub_f32_e32 v228, v228, v242
	v_sub_f32_e32 v229, v229, v242
	v_sub_f32_e32 v230, v230, v242
	v_sub_f32_e32 v231, v231, v242
	v_sub_f32_e32 v232, v232, v242
	v_sub_f32_e32 v233, v233, v242
	v_sub_f32_e32 v234, v234, v242
	v_sub_f32_e32 v235, v235, v242
	v_sub_f32_e32 v236, v236, v242
	v_sub_f32_e32 v237, v237, v242
	v_sub_f32_e32 v238, v238, v242
	v_sub_f32_e32 v239, v239, v242
	v_sub_f32_e32 v240, v240, v242
	v_sub_f32_e32 v241, v241, v242
	s_branch .LBB0_119

; __device__ __forceinline__ void finishSM(f32x16& p0, f32x16& p1, float alpha, float& l_reg, bf16x8& pa0, bf16x8& pa1, bf16x8& pa2, bf16x8& pa3) {
; #pragma unroll
;   for (int r = 0; r < 16; ++r) p1[r] = __builtin_amdgcn_exp2f(p1[r]);
;   float ps = 0;
; #pragma unroll
;   for (int r = 0; r < 16; ++r) ps += p0[r];
; #pragma unroll
;   for (int r = 0; r < 16; ++r) ps += p1[r];
;   { auto rr = __builtin_amdgcn_permlane32_swap(__float_as_uint(ps), __float_as_uint(ps), false, false);
;     ps = __uint_as_float(rr[0]) + __uint_as_float(rr[1]); }
;   l_reg = l_reg * alpha + ps;
;     ...
;   PK4(p0, 0, pa0); PK4(p0, 8, pa1); PK4(p1, 0, pa2); PK4(p1, 8, pa3);
;     ...
; }
; template <int BUFOFF>
; __device__ __forceinline__ void qkt_diff(f32x16& p0, f32x16& p1, const int* ka, const bf16x8* qr) {
;   typedef __attribute__((address_space(3))) const bf16x8* lp;
;   p0 = f32x16{}; p1 = f32x16{};
; #pragma unroll
;   for (int d0 = 0; d0 < 4; ++d0) {
;     const int a = ka[d0] + BUFOFF;
;     const bf16x8 b0 = *(lp)(a), b1 = *(lp)(a + 8192);
;     p0 = __builtin_amdgcn_mfma_f32_32x32x16_bf16(b0, qr[d0], p0, 0, 0, 0);
;     p1 = __builtin_amdgcn_mfma_f32_32x32x16_bf16(b1, qr[d0], p1, 0, 0, 0);
;   }
; }
.LBB0_129:
	s_mov_b32 s54, s47
	s_mov_b32 s47, s52
	ds_read_b128 v[64:67], v138 offset:16384
	ds_read_b128 v[68:71], v138 offset:24576
	ds_read_b128 v[170:173], v141 offset:16384
	ds_read_b128 v[188:191], v141 offset:24576
	s_waitcnt lgkmcnt(0)
	v_mfma_f32_32x32x16_bf16 v[80:95], v[64:67], v[108:111], v[226:241]
	v_add_f32_e32 v112, v144, v113
	v_mfma_f32_32x32x16_bf16 v[64:79], v[68:71], v[108:111], v[226:241]
	v_add_f32_e32 v243, v148, v155
	v_add_f32_e32 v244, v145, v152
	v_add_f32_e32 v245, v149, v156
	v_add_f32_e32 v246, v146, v153
	v_add_f32_e32 v247, v150, v158
	v_mfma_f32_32x32x16_bf16 v[80:95], v[170:173], v[104:107], v[80:95]
	v_add_f32_e32 v251, v147, v154
	v_add_f32_e32 v252, v151, v159
	v_mov_b32_e32 v132, v124
	v_add_f32_e32 v112, v128, v112
	v_mov_b32_e32 v162, v125
	v_mfma_f32_32x32x16_bf16 v[64:79], v[188:191], v[104:107], v[64:79]
	ds_read_b128 v[170:173], v140 offset:16384
	ds_read_b128 v[188:191], v140 offset:24576
	v_add_f32_e32 v243, v129, v243
	v_mov_b32_e32 v167, v120
	v_add_f32_e32 v244, v126, v244
	v_mov_b32_e32 v169, v121
	v_add_f32_e32 v245, v127, v245
	v_add_f32_e32 v246, v132, v246
	s_waitcnt lgkmcnt(0)
	v_mfma_f32_32x32x16_bf16 v[80:95], v[170:173], v[100:103], v[80:95]
	v_add_f32_e32 v247, v162, v247
	v_add_f32_e32 v251, v167, v251
	v_add_f32_e32 v252, v169, v252
	v_mfma_f32_32x32x16_bf16 v[64:79], v[188:191], v[100:103], v[64:79]
	ds_read_b128 v[170:173], v139 offset:16384
	ds_read_b128 v[188:191], v139 offset:24576
	s_waitcnt lgkmcnt(0)
	v_mfma_f32_32x32x16_bf16 v[80:95], v[170:173], v[96:99], v[80:95]
	v_mov_b32_e32 v170, v118
	v_mov_b32_e32 v171, v117
	v_mov_b32_e32 v172, v114
	v_mov_b32_e32 v173, v115
	v_add_f32_e32 v112, v170, v112
	v_add_f32_e32 v243, v119, v243
	v_add_f32_e32 v244, v116, v244
	v_mfma_f32_32x32x16_bf16 v[64:79], v[188:191], v[96:99], v[64:79]
	v_mov_b32_e32 v188, v122
	v_mov_b32_e32 v189, v123
	v_add_f32_e32 v245, v171, v245
	v_add_f32_e32 v246, v172, v246
	v_add_f32_e32 v247, v173, v247
	v_add_f32_e32 v251, v188, v251
	v_add_f32_e32 v252, v189, v252
	v_add_f32_e32 v112, v112, v243
	v_add_f32_e32 v244, v244, v245
	v_add_f32_e32 v246, v246, v247
	v_add_f32_e32 v251, v251, v252
	v_add_f32_e32 v112, v112, v244
	v_add_f32_e32 v246, v246, v251
	v_add_f32_e32 v117, v112, v246
	v_mov_b32_e32 v118, v117
	v_cvt_pk_bf16_f32 v112, v113, v155
	v_cvt_pk_bf16_f32 v113, v152, v156
	v_cvt_pk_bf16_f32 v114, v153, v158
	s_nop 1
	v_permlane32_swap_b32_e32 v117, v118
	v_cvt_pk_bf16_f32 v115, v154, v159
	v_cvt_pk_bf16_f32 v120, v144, v148
	v_cvt_pk_bf16_f32 v121, v145, v149
	v_cvt_pk_bf16_f32 v122, v146, v150
	v_cvt_pk_bf16_f32 v123, v147, v151
	v_cvt_pk_bf16_f32 v124, v128, v129
	v_cvt_pk_bf16_f32 v125, v126, v127
	v_cvt_pk_bf16_f32 v126, v132, v162
	v_cvt_pk_bf16_f32 v127, v167, v169
	v_cvt_pk_bf16_f32 v144, v170, v119
	v_cvt_pk_bf16_f32 v145, v116, v171
	v_cvt_pk_bf16_f32 v146, v172, v173
	v_cvt_pk_bf16_f32 v147, v188, v189
	s_lshl_b32 s101, s47, 14
	v_add_u32_e32 v132, s101, v133
	ds_read_b64_tr_b16 v[148:149], v132 offset:0
	ds_read_b64_tr_b16 v[150:151], v132 offset:0x800
	ds_read_b64_tr_b16 v[152:153], v132 offset:0x1000
	ds_read_b64_tr_b16 v[154:155], v132 offset:0x1800
	ds_read_b64_tr_b16 v[170:171], v132 offset:0x2000
	ds_read_b64_tr_b16 v[172:173], v132 offset:0x2800
	ds_read_b64_tr_b16 v[188:189], v132 offset:0x3000
	ds_read_b64_tr_b16 v[190:191], v132 offset:0x3800
	s_add_u32 s4, s14, 0x2000000
	s_mov_b32 m0, s43
	s_addc_u32 s5, s15, 0
	s_mov_b64 s[56:57], s[14:15]
	s_lshl_b32 s52, s53, 14
	s_add_i32 s55, s42, s52
	s_nop 0
	global_load_lds_dwordx4 v134, s[56:57]
	s_mov_b32 m0, s44
	s_nop 0
	global_load_lds_dwordx4 v135, s[56:57]
	s_mov_b32 m0, s55
	s_nop 0
	global_load_lds_dwordx4 v136, s[4:5]
	s_add_i32 m0, s55, 0x2000
	s_nop 0
	global_load_lds_dwordx4 v137, s[4:5]
	s_lshl_b32 s55, s47, 14
	s_nop 0
	s_waitcnt lgkmcnt(6)
	v_mfma_f32_32x32x16_bf16 v[32:47], v[148:151], v[112:115], v[32:47]
	ds_read_b64_tr_b16 v[148:149], v132 offset:0x200
	ds_read_b64_tr_b16 v[150:151], v132 offset:0xa00
	s_waitcnt lgkmcnt(6)
	v_mfma_f32_32x32x16_bf16 v[32:47], v[152:155], v[120:123], v[32:47]
	ds_read_b64_tr_b16 v[152:153], v132 offset:0x1200
	ds_read_b64_tr_b16 v[154:155], v132 offset:0x1a00
	s_waitcnt lgkmcnt(6)
	v_mfma_f32_32x32x16_bf16 v[32:47], v[170:173], v[124:127], v[32:47]
	ds_read_b64_tr_b16 v[170:171], v132 offset:0x2200
	ds_read_b64_tr_b16 v[172:173], v132 offset:0x2a00
	s_waitcnt lgkmcnt(6)
	v_mfma_f32_32x32x16_bf16 v[32:47], v[188:191], v[144:147], v[32:47]
	ds_read_b64_tr_b16 v[188:189], v132 offset:0x3200
	ds_read_b64_tr_b16 v[190:191], v132 offset:0x3a00
	s_waitcnt lgkmcnt(6)
	v_mfma_f32_32x32x16_bf16 v[48:63], v[148:151], v[112:115], v[48:63]
	ds_read_b64_tr_b16 v[148:149], v132 offset:0x400
	ds_read_b64_tr_b16 v[150:151], v132 offset:0xc00
	s_waitcnt lgkmcnt(6)
	v_mfma_f32_32x32x16_bf16 v[48:63], v[152:155], v[120:123], v[48:63]
	ds_read_b64_tr_b16 v[152:153], v132 offset:0x1400
	ds_read_b64_tr_b16 v[154:155], v132 offset:0x1c00
	s_waitcnt lgkmcnt(6)
	v_mfma_f32_32x32x16_bf16 v[48:63], v[170:173], v[124:127], v[48:63]
	ds_read_b64_tr_b16 v[170:171], v132 offset:0x2400
	ds_read_b64_tr_b16 v[172:173], v132 offset:0x2c00
	s_waitcnt lgkmcnt(6)
	v_mfma_f32_32x32x16_bf16 v[48:63], v[188:191], v[144:147], v[48:63]
	ds_read_b64_tr_b16 v[188:189], v132 offset:0x3400
	ds_read_b64_tr_b16 v[190:191], v132 offset:0x3c00
	s_waitcnt lgkmcnt(6)
; #define SBAR() __builtin_amdgcn_sched_barrier(0)
; template <int MLA>
; __device__ __forceinline__ void partialSM(f32x16& p0, f32x16& p1, float& m_reg, float& mn, float& alpha) {
;   constexpr float SCALE = AttC<MLA>::SCALE;
;   constexpr float C = SCALE * 1.4426950408889634f;
;   float pmax = p0[0];
; #pragma unroll
;   for (int r = 1; r < 16; ++r) pmax = fmaxf(pmax, p0[r]);
; #pragma unroll
;   for (int r = 0; r < 16; ++r) pmax = fmaxf(pmax, p1[r]);
;   { auto rr = __builtin_amdgcn_permlane32_swap(__float_as_uint(pmax), __float_as_uint(pmax), false, false);
;     pmax = fmaxf(__uint_as_float(rr[0]), __uint_as_float(rr[1])); }
;   if (__builtin_expect(__all(pmax - m_reg <= THR / SCALE), 1)) { mn = m_reg; alpha = 1.f; }
;   else { mn = fmaxf(m_reg, pmax); alpha = __builtin_amdgcn_exp2f((m_reg - mn) * C); m_reg = mn; }
;   float mnC = -mn * C;
; #pragma unroll
;   for (int r = 0; r < 16; ++r) p0[r] = fmaf(p0[r], C, mnC);
; #pragma unroll
;   for (int r = 0; r < 16; ++r) p1[r] = fmaf(p1[r], C, mnC);
; #pragma unroll
;   for (int r = 0; r < 16; ++r) p0[r] = __builtin_amdgcn_exp2f(p0[r]);
; }
; template <int D0> __device__ __forceinline__ void pv_one_t(f32x16& od, int vb, bf16x8 pa0, bf16x8 pa1, bf16x8 pa2, bf16x8 pa3) {
;   const s16x4 l0 = tr_read<v_rd_off(D0, 0, 0)>(vb), h0 = tr_read<v_rd_off(D0, 0, 1)>(vb), l1 = tr_read<v_rd_off(D0, 1, 0)>(vb), h1 = tr_read<v_rd_off(D0, 1, 1)>(vb);
;   const s16x4 l2 = tr_read<v_rd_off(D0, 2, 0)>(vb), h2 = tr_read<v_rd_off(D0, 2, 1)>(vb), l3 = tr_read<v_rd_off(D0, 3, 0)>(vb), h3 = tr_read<v_rd_off(D0, 3, 1)>(vb);
;   asm volatile("s_waitcnt lgkmcnt(0)" ::: "memory"); SBAR();
;     ...
;   od = __builtin_amdgcn_mfma_f32_32x32x16_bf16(PK(l0, h0), pa0, od, 0, 0, 0);
;   od = __builtin_amdgcn_mfma_f32_32x32x16_bf16(PK(l1, h1), pa1, od, 0, 0, 0);
;   od = __builtin_amdgcn_mfma_f32_32x32x16_bf16(PK(l2, h2), pa2, od, 0, 0, 0);
;   od = __builtin_amdgcn_mfma_f32_32x32x16_bf16(PK(l3, h3), pa3, od, 0, 0, 0);
;     ...
; }
; __device__ __forceinline__ void pv_d0_t(f32x16* o, int vb, bf16x8 pa0, bf16x8 pa1, bf16x8 pa2, bf16x8 pa3) {
;   pv_one_t<0>(o[0], vb, pa0, pa1, pa2, pa3); pv_one_t<1>(o[1], vb, pa0, pa1, pa2, pa3); pv_one_t<2>(o[2], vb, pa0, pa1, pa2, pa3); pv_one_t<3>(o[3], vb, pa0, pa1, pa2, pa3);
; }
	v_mfma_f32_32x32x16_bf16 v[16:31], v[148:151], v[112:115], v[16:31]
	ds_read_b64_tr_b16 v[148:149], v132 offset:0x600
	ds_read_b64_tr_b16 v[150:151], v132 offset:0xe00
	s_waitcnt lgkmcnt(6)
	v_mfma_f32_32x32x16_bf16 v[16:31], v[152:155], v[120:123], v[16:31]
	ds_read_b64_tr_b16 v[152:153], v132 offset:0x1600
	ds_read_b64_tr_b16 v[154:155], v132 offset:0x1e00
	s_waitcnt lgkmcnt(6)
	v_mfma_f32_32x32x16_bf16 v[16:31], v[170:173], v[124:127], v[16:31]
	ds_read_b64_tr_b16 v[170:171], v132 offset:0x2600
	ds_read_b64_tr_b16 v[172:173], v132 offset:0x2e00
	s_waitcnt lgkmcnt(6)
	v_mfma_f32_32x32x16_bf16 v[16:31], v[188:191], v[144:147], v[16:31]
	ds_read_b64_tr_b16 v[188:189], v132 offset:0x3600
	ds_read_b64_tr_b16 v[190:191], v132 offset:0x3e00
	s_waitcnt lgkmcnt(6)
	v_mfma_f32_32x32x16_bf16 v[0:15], v[148:151], v[112:115], v[0:15]
	v_max_f32_e32 v112, v80, v81
	v_max3_f32 v112, v112, v82, v83
	v_max3_f32 v112, v112, v84, v85
	v_max3_f32 v112, v112, v86, v87
	v_max3_f32 v112, v112, v88, v89
	v_max3_f32 v112, v112, v90, v91
	v_max3_f32 v112, v112, v92, v93
	s_waitcnt lgkmcnt(4)
	v_mfma_f32_32x32x16_bf16 v[0:15], v[152:155], v[120:123], v[0:15]
	v_max3_f32 v112, v112, v94, v95
	v_max3_f32 v112, v112, v64, v65
	v_max3_f32 v112, v112, v66, v67
	v_max3_f32 v112, v112, v68, v69
	v_max3_f32 v112, v112, v70, v71
	v_max3_f32 v112, v112, v72, v73
	v_max3_f32 v112, v112, v74, v75
	v_max3_f32 v112, v112, v76, v77
	s_waitcnt lgkmcnt(2)
	v_mfma_f32_32x32x16_bf16 v[0:15], v[170:173], v[124:127], v[0:15]
	v_max3_f32 v112, v112, v78, v79
	v_mov_b32_e32 v113, v112
	s_nop 1
	v_permlane32_swap_b32_e32 v112, v113
	v_max_f32_e32 v112, v112, v113
	v_cmp_ge_f32_e32 vcc, s70, v112
	s_waitcnt lgkmcnt(0)
	v_mfma_f32_32x32x16_bf16 v[0:15], v[188:191], v[144:147], v[0:15]
	s_cmp_eq_u64 vcc, exec
	s_cselect_b64 s[4:5], -1, 0
	s_waitcnt vmcnt(0) lgkmcnt(0)
	s_barrier
	s_cbranch_scc1 .Lal_c_d1
	v_max_f32_e32 v242, 0, v112
	v_exp_f32_e64 v116, -v242
	s_nop 0
	v_pk_mul_f32 v[46:47], v[46:47], v[116:117] op_sel_hi:[1,0]
	v_pk_mul_f32 v[44:45], v[44:45], v[116:117] op_sel_hi:[1,0]
	v_pk_mul_f32 v[42:43], v[42:43], v[116:117] op_sel_hi:[1,0]
	v_pk_mul_f32 v[40:41], v[40:41], v[116:117] op_sel_hi:[1,0]
	v_pk_mul_f32 v[38:39], v[38:39], v[116:117] op_sel_hi:[1,0]
	v_pk_mul_f32 v[36:37], v[36:37], v[116:117] op_sel_hi:[1,0]
	v_pk_mul_f32 v[34:35], v[34:35], v[116:117] op_sel_hi:[1,0]
	v_pk_mul_f32 v[32:33], v[32:33], v[116:117] op_sel_hi:[1,0]
	v_pk_mul_f32 v[62:63], v[62:63], v[116:117] op_sel_hi:[1,0]
	v_pk_mul_f32 v[60:61], v[60:61], v[116:117] op_sel_hi:[1,0]
	v_pk_mul_f32 v[58:59], v[58:59], v[116:117] op_sel_hi:[1,0]
	v_pk_mul_f32 v[56:57], v[56:57], v[116:117] op_sel_hi:[1,0]
	v_pk_mul_f32 v[54:55], v[54:55], v[116:117] op_sel_hi:[1,0]
	v_pk_mul_f32 v[52:53], v[52:53], v[116:117] op_sel_hi:[1,0]
	v_pk_mul_f32 v[50:51], v[50:51], v[116:117] op_sel_hi:[1,0]
	v_pk_mul_f32 v[48:49], v[48:49], v[116:117] op_sel_hi:[1,0]
	v_pk_mul_f32 v[30:31], v[30:31], v[116:117] op_sel_hi:[1,0]
	v_pk_mul_f32 v[28:29], v[28:29], v[116:117] op_sel_hi:[1,0]
	v_pk_mul_f32 v[26:27], v[26:27], v[116:117] op_sel_hi:[1,0]
	v_pk_mul_f32 v[24:25], v[24:25], v[116:117] op_sel_hi:[1,0]
	v_pk_mul_f32 v[22:23], v[22:23], v[116:117] op_sel_hi:[1,0]
	v_pk_mul_f32 v[20:21], v[20:21], v[116:117] op_sel_hi:[1,0]
	v_pk_mul_f32 v[18:19], v[18:19], v[116:117] op_sel_hi:[1,0]
	v_pk_mul_f32 v[16:17], v[16:17], v[116:117] op_sel_hi:[1,0]
	v_pk_mul_f32 v[14:15], v[14:15], v[116:117] op_sel_hi:[1,0]
	v_pk_mul_f32 v[12:13], v[12:13], v[116:117] op_sel_hi:[1,0]
	v_pk_mul_f32 v[10:11], v[10:11], v[116:117] op_sel_hi:[1,0]
	v_pk_mul_f32 v[8:9], v[8:9], v[116:117] op_sel_hi:[1,0]
	v_pk_mul_f32 v[6:7], v[6:7], v[116:117] op_sel_hi:[1,0]
	v_pk_mul_f32 v[4:5], v[4:5], v[116:117] op_sel_hi:[1,0]
	v_pk_mul_f32 v[2:3], v[2:3], v[116:117] op_sel_hi:[1,0]
	v_pk_mul_f32 v[0:1], v[0:1], v[116:117] op_sel_hi:[1,0]
	v_sub_f32_e32 v80, v80, v242
	v_sub_f32_e32 v81, v81, v242
	v_sub_f32_e32 v82, v82, v242
	v_sub_f32_e32 v83, v83, v242
	v_sub_f32_e32 v84, v84, v242
	v_sub_f32_e32 v85, v85, v242
	v_sub_f32_e32 v86, v86, v242
	v_sub_f32_e32 v87, v87, v242
	v_sub_f32_e32 v88, v88, v242
	v_sub_f32_e32 v89, v89, v242
	v_sub_f32_e32 v90, v90, v242
	v_sub_f32_e32 v91, v91, v242
	v_sub_f32_e32 v92, v92, v242
	v_sub_f32_e32 v93, v93, v242
	v_sub_f32_e32 v94, v94, v242
	v_sub_f32_e32 v95, v95, v242
	v_sub_f32_e32 v64, v64, v242
	v_sub_f32_e32 v65, v65, v242
	v_sub_f32_e32 v66, v66, v242
	v_sub_f32_e32 v67, v67, v242
	v_sub_f32_e32 v68, v68, v242
	v_sub_f32_e32 v69, v69, v242
	v_sub_f32_e32 v70, v70, v242
	v_sub_f32_e32 v71, v71, v242
	v_sub_f32_e32 v72, v72, v242
	v_sub_f32_e32 v73, v73, v242
	v_sub_f32_e32 v74, v74, v242
	v_sub_f32_e32 v75, v75, v242
	v_sub_f32_e32 v76, v76, v242
	v_sub_f32_e32 v77, v77, v242
	v_sub_f32_e32 v78, v78, v242
	v_sub_f32_e32 v79, v79, v242
	v_sub_f32_e32 v226, v226, v242
	v_sub_f32_e32 v227, v227, v242
	v_sub_f32_e32 v228, v228, v242
	v_sub_f32_e32 v229, v229, v242
	v_sub_f32_e32 v230, v230, v242
	v_sub_f32_e32 v231, v231, v242
	v_sub_f32_e32 v232, v232, v242
	v_sub_f32_e32 v233, v233, v242
	v_sub_f32_e32 v234, v234, v242
	v_sub_f32_e32 v235, v235, v242
	v_sub_f32_e32 v236, v236, v242
	v_sub_f32_e32 v237, v237, v242
	v_sub_f32_e32 v238, v238, v242
	v_sub_f32_e32 v239, v239, v242
	v_sub_f32_e32 v240, v240, v242
	v_sub_f32_e32 v241, v241, v242
	s_branch .LBB0_131

; __device__ __forceinline__ void finishSM(f32x16& p0, f32x16& p1, float alpha, float& l_reg, bf16x8& pa0, bf16x8& pa1, bf16x8& pa2, bf16x8& pa3) {
; #pragma unroll
;   for (int r = 0; r < 16; ++r) p1[r] = __builtin_amdgcn_exp2f(p1[r]);
;   float ps = 0;
; #pragma unroll
;   for (int r = 0; r < 16; ++r) ps += p0[r];
; #pragma unroll
;   for (int r = 0; r < 16; ++r) ps += p1[r];
;   { auto rr = __builtin_amdgcn_permlane32_swap(__float_as_uint(ps), __float_as_uint(ps), false, false);
;     ps = __uint_as_float(rr[0]) + __uint_as_float(rr[1]); }
;   l_reg = l_reg * alpha + ps;
;     ...
;   PK4(p0, 0, pa0); PK4(p0, 8, pa1); PK4(p1, 0, pa2); PK4(p1, 8, pa3);
;     ...
; }
; template <int BUFOFF>
; __device__ __forceinline__ void qkt_diff(f32x16& p0, f32x16& p1, const int* ka, const bf16x8* qr) {
;   typedef __attribute__((address_space(3))) const bf16x8* lp;
;   p0 = f32x16{}; p1 = f32x16{};
; #pragma unroll
;   for (int d0 = 0; d0 < 4; ++d0) {
;     const int a = ka[d0] + BUFOFF;
;     const bf16x8 b0 = *(lp)(a), b1 = *(lp)(a + 8192);
;     p0 = __builtin_amdgcn_mfma_f32_32x32x16_bf16(b0, qr[d0], p0, 0, 0, 0);
;     p1 = __builtin_amdgcn_mfma_f32_32x32x16_bf16(b1, qr[d0], p1, 0, 0, 0);
;   }
; }
.LBB0_131:
	v_exp_f32_e32 v125, v64
	v_exp_f32_e32 v126, v65
	v_exp_f32_e32 v127, v66
	v_exp_f32_e32 v128, v67
	v_exp_f32_e32 v129, v68
	v_exp_f32_e32 v143, v69
	v_exp_f32_e32 v144, v70
	v_exp_f32_e32 v145, v71
	v_exp_f32_e32 v146, v72
	v_exp_f32_e32 v147, v73
	v_exp_f32_e32 v148, v74
	v_exp_f32_e32 v149, v75
	v_exp_f32_e32 v150, v76
	v_exp_f32_e32 v151, v80
	v_exp_f32_e32 v152, v81
	v_exp_f32_e32 v153, v82
	v_exp_f32_e32 v154, v83
	v_exp_f32_e32 v155, v84
	v_exp_f32_e32 v156, v85
	v_exp_f32_e32 v158, v86
	v_exp_f32_e32 v159, v87
	v_exp_f32_e32 v162, v88
	v_exp_f32_e32 v167, v89
	v_exp_f32_e32 v169, v90
	v_exp_f32_e32 v170, v91
	v_exp_f32_e32 v171, v92
	v_exp_f32_e32 v172, v93
	v_exp_f32_e32 v173, v94
	v_exp_f32_e32 v188, v95
	v_exp_f32_e32 v189, v77
	v_exp_f32_e32 v190, v78
	v_exp_f32_e32 v124, v79
	ds_read_b128 v[64:67], v138
	ds_read_b128 v[68:71], v138 offset:8192
	ds_read_b128 v[112:115], v141
	ds_read_b128 v[120:123], v141 offset:8192
	v_mov_b32_e32 v191, v125
	s_waitcnt lgkmcnt(0)
	v_mfma_f32_32x32x16_bf16 v[80:95], v[64:67], v[108:111], v[226:241]
	v_mfma_f32_32x32x16_bf16 v[64:79], v[68:71], v[108:111], v[226:241]
	v_mov_b32_e32 v192, v124
	v_mfma_f32_32x32x16_bf16 v[80:95], v[112:115], v[104:107], v[80:95]
	v_mfma_f32_32x32x16_bf16 v[64:79], v[120:123], v[104:107], v[64:79]
	ds_read_b128 v[112:115], v140
	ds_read_b128 v[120:123], v140 offset:8192
	s_waitcnt lgkmcnt(0)
	v_mfma_f32_32x32x16_bf16 v[80:95], v[112:115], v[100:103], v[80:95]
	v_mfma_f32_32x32x16_bf16 v[64:79], v[120:123], v[100:103], v[64:79]
	ds_read_b128 v[112:115], v139
	ds_read_b128 v[120:123], v139 offset:8192
	s_waitcnt lgkmcnt(0)
	v_mfma_f32_32x32x16_bf16 v[80:95], v[112:115], v[96:99], v[80:95]
	v_add_f32_e32 v112, v162, v151
	v_add_f32_e32 v243, v167, v152
	v_add_f32_e32 v244, v169, v153
	v_add_f32_e32 v245, v170, v154
	v_add_f32_e32 v246, v171, v155
	v_add_f32_e32 v247, v172, v156
	v_add_f32_e32 v251, v173, v158
	v_add_f32_e32 v252, v188, v159
	v_add_f32_e32 v112, v191, v112
	v_add_f32_e32 v243, v126, v243
	v_add_f32_e32 v244, v127, v244
	v_add_f32_e32 v245, v128, v245
	v_add_f32_e32 v246, v129, v246
	v_add_f32_e32 v247, v143, v247
	v_add_f32_e32 v251, v144, v251
	v_add_f32_e32 v252, v145, v252
	v_add_f32_e32 v112, v146, v112
	v_add_f32_e32 v243, v147, v243
	v_mfma_f32_32x32x16_bf16 v[64:79], v[120:123], v[96:99], v[64:79]
	v_add_f32_e32 v244, v148, v244
	v_add_f32_e32 v245, v149, v245
	v_add_f32_e32 v246, v150, v246
	v_add_f32_e32 v247, v189, v247
	v_add_f32_e32 v251, v190, v251
	v_add_f32_e32 v252, v192, v252
	v_add_f32_e32 v112, v112, v243
	v_add_f32_e32 v244, v244, v245
	v_add_f32_e32 v246, v246, v247
	v_add_f32_e32 v251, v251, v252
	v_add_f32_e32 v112, v112, v244
	v_add_f32_e32 v246, v246, v251
	v_add_f32_e32 v120, v112, v246
	v_mov_b32_e32 v121, v120
	v_cvt_pk_bf16_f32 v112, v151, v152
	v_cvt_pk_bf16_f32 v113, v153, v154
	v_cvt_pk_bf16_f32 v114, v155, v156
	v_cvt_pk_bf16_f32 v115, v158, v159
	s_nop 1
	v_permlane32_swap_b32_e32 v120, v121
	v_cvt_pk_bf16_f32 v122, v162, v167
	v_cvt_pk_bf16_f32 v123, v169, v170
	v_cvt_pk_bf16_f32 v124, v171, v172
	v_cvt_pk_bf16_f32 v125, v173, v188
	v_cvt_pk_bf16_f32 v126, v191, v126
	v_cvt_pk_bf16_f32 v127, v127, v128
	v_cvt_pk_bf16_f32 v128, v129, v143
	v_cvt_pk_bf16_f32 v129, v144, v145
	v_cvt_pk_bf16_f32 v144, v146, v147
	v_cvt_pk_bf16_f32 v145, v148, v149
	v_cvt_pk_bf16_f32 v146, v150, v189
	v_cvt_pk_bf16_f32 v147, v190, v192
	v_lshl_add_u32 v143, s54, 14, v133
	ds_read_b64_tr_b16 v[148:149], v143 offset:0
	ds_read_b64_tr_b16 v[150:151], v143 offset:0x800
	ds_read_b64_tr_b16 v[152:153], v143 offset:0x1000
	ds_read_b64_tr_b16 v[154:155], v143 offset:0x1800
	ds_read_b64_tr_b16 v[170:171], v143 offset:0x2000
	ds_read_b64_tr_b16 v[172:173], v143 offset:0x2800
	ds_read_b64_tr_b16 v[188:189], v143 offset:0x3000
	ds_read_b64_tr_b16 v[190:191], v143 offset:0x3800
	s_nop 0
	s_add_u32 s4, s14, 0x20000
	s_addc_u32 s5, s15, 0
	s_add_u32 s56, s14, 0x2020000
	s_mov_b32 m0, s16
	s_addc_u32 s57, s15, 0
	s_add_i32 s55, s42, s55
	s_nop 0
	global_load_lds_dwordx4 v134, s[4:5]
	s_mov_b32 m0, s17
	s_nop 0
	global_load_lds_dwordx4 v135, s[4:5]
	s_mov_b32 m0, s55
	s_nop 0
	global_load_lds_dwordx4 v136, s[56:57]
	s_add_i32 m0, s55, 0x2000
	s_nop 0
	global_load_lds_dwordx4 v137, s[56:57]
	s_nop 0
	s_waitcnt lgkmcnt(6)
	v_mfma_f32_32x32x16_bf16 v[32:47], v[148:151], v[112:115], v[32:47]
	ds_read_b64_tr_b16 v[148:149], v143 offset:0x200
	ds_read_b64_tr_b16 v[150:151], v143 offset:0xa00
	s_waitcnt lgkmcnt(6)
	v_mfma_f32_32x32x16_bf16 v[32:47], v[152:155], v[122:125], v[32:47]
	ds_read_b64_tr_b16 v[152:153], v143 offset:0x1200
	ds_read_b64_tr_b16 v[154:155], v143 offset:0x1a00
	s_waitcnt lgkmcnt(6)
	v_mfma_f32_32x32x16_bf16 v[32:47], v[170:173], v[126:129], v[32:47]
	ds_read_b64_tr_b16 v[170:171], v143 offset:0x2200
	ds_read_b64_tr_b16 v[172:173], v143 offset:0x2a00
	s_waitcnt lgkmcnt(6)
	v_mfma_f32_32x32x16_bf16 v[32:47], v[188:191], v[144:147], v[32:47]
	ds_read_b64_tr_b16 v[188:189], v143 offset:0x3200
	ds_read_b64_tr_b16 v[190:191], v143 offset:0x3a00
	s_waitcnt lgkmcnt(6)
	v_mfma_f32_32x32x16_bf16 v[48:63], v[148:151], v[112:115], v[48:63]
	ds_read_b64_tr_b16 v[148:149], v143 offset:0x400
	ds_read_b64_tr_b16 v[150:151], v143 offset:0xc00
	s_waitcnt lgkmcnt(6)
	v_mfma_f32_32x32x16_bf16 v[48:63], v[152:155], v[122:125], v[48:63]
	ds_read_b64_tr_b16 v[152:153], v143 offset:0x1400
	ds_read_b64_tr_b16 v[154:155], v143 offset:0x1c00
	s_waitcnt lgkmcnt(6)
	v_mfma_f32_32x32x16_bf16 v[48:63], v[170:173], v[126:129], v[48:63]
	ds_read_b64_tr_b16 v[170:171], v143 offset:0x2400
	ds_read_b64_tr_b16 v[172:173], v143 offset:0x2c00
	s_waitcnt lgkmcnt(6)
; #define SBAR() __builtin_amdgcn_sched_barrier(0)
; template <int MLA>
; __device__ __forceinline__ void partialSM(f32x16& p0, f32x16& p1, float& m_reg, float& mn, float& alpha) {
;   constexpr float SCALE = AttC<MLA>::SCALE;
;   constexpr float C = SCALE * 1.4426950408889634f;
;   float pmax = p0[0];
; #pragma unroll
;   for (int r = 1; r < 16; ++r) pmax = fmaxf(pmax, p0[r]);
; #pragma unroll
;   for (int r = 0; r < 16; ++r) pmax = fmaxf(pmax, p1[r]);
;   { auto rr = __builtin_amdgcn_permlane32_swap(__float_as_uint(pmax), __float_as_uint(pmax), false, false);
;     pmax = fmaxf(__uint_as_float(rr[0]), __uint_as_float(rr[1])); }
;   if (__builtin_expect(__all(pmax - m_reg <= THR / SCALE), 1)) { mn = m_reg; alpha = 1.f; }
;   else { mn = fmaxf(m_reg, pmax); alpha = __builtin_amdgcn_exp2f((m_reg - mn) * C); m_reg = mn; }
;   float mnC = -mn * C;
; #pragma unroll
;   for (int r = 0; r < 16; ++r) p0[r] = fmaf(p0[r], C, mnC);
; #pragma unroll
;   for (int r = 0; r < 16; ++r) p1[r] = fmaf(p1[r], C, mnC);
; #pragma unroll
;   for (int r = 0; r < 16; ++r) p0[r] = __builtin_amdgcn_exp2f(p0[r]);
; }
; template <int D0> __device__ __forceinline__ void pv_one_t(f32x16& od, int vb, bf16x8 pa0, bf16x8 pa1, bf16x8 pa2, bf16x8 pa3) {
;   const s16x4 l0 = tr_read<v_rd_off(D0, 0, 0)>(vb), h0 = tr_read<v_rd_off(D0, 0, 1)>(vb), l1 = tr_read<v_rd_off(D0, 1, 0)>(vb), h1 = tr_read<v_rd_off(D0, 1, 1)>(vb);
;   const s16x4 l2 = tr_read<v_rd_off(D0, 2, 0)>(vb), h2 = tr_read<v_rd_off(D0, 2, 1)>(vb), l3 = tr_read<v_rd_off(D0, 3, 0)>(vb), h3 = tr_read<v_rd_off(D0, 3, 1)>(vb);
;   asm volatile("s_waitcnt lgkmcnt(0)" ::: "memory"); SBAR();
;     ...
;   od = __builtin_amdgcn_mfma_f32_32x32x16_bf16(PK(l0, h0), pa0, od, 0, 0, 0);
;   od = __builtin_amdgcn_mfma_f32_32x32x16_bf16(PK(l1, h1), pa1, od, 0, 0, 0);
;   od = __builtin_amdgcn_mfma_f32_32x32x16_bf16(PK(l2, h2), pa2, od, 0, 0, 0);
;   od = __builtin_amdgcn_mfma_f32_32x32x16_bf16(PK(l3, h3), pa3, od, 0, 0, 0);
;     ...
; }
; __device__ __forceinline__ void pv_d0_t(f32x16* o, int vb, bf16x8 pa0, bf16x8 pa1, bf16x8 pa2, bf16x8 pa3) {
;   pv_one_t<0>(o[0], vb, pa0, pa1, pa2, pa3); pv_one_t<1>(o[1], vb, pa0, pa1, pa2, pa3); pv_one_t<2>(o[2], vb, pa0, pa1, pa2, pa3); pv_one_t<3>(o[3], vb, pa0, pa1, pa2, pa3);
; }
	v_mfma_f32_32x32x16_bf16 v[48:63], v[188:191], v[144:147], v[48:63]
	ds_read_b64_tr_b16 v[188:189], v143 offset:0x3400
	ds_read_b64_tr_b16 v[190:191], v143 offset:0x3c00
	s_waitcnt lgkmcnt(6)
	v_mfma_f32_32x32x16_bf16 v[16:31], v[148:151], v[112:115], v[16:31]
	ds_read_b64_tr_b16 v[148:149], v143 offset:0x600
	ds_read_b64_tr_b16 v[150:151], v143 offset:0xe00
	s_waitcnt lgkmcnt(6)
	v_mfma_f32_32x32x16_bf16 v[16:31], v[152:155], v[122:125], v[16:31]
	ds_read_b64_tr_b16 v[152:153], v143 offset:0x1600
	ds_read_b64_tr_b16 v[154:155], v143 offset:0x1e00
	s_waitcnt lgkmcnt(6)
	v_mfma_f32_32x32x16_bf16 v[16:31], v[170:173], v[126:129], v[16:31]
	ds_read_b64_tr_b16 v[170:171], v143 offset:0x2600
	ds_read_b64_tr_b16 v[172:173], v143 offset:0x2e00
	s_waitcnt lgkmcnt(6)
	v_mfma_f32_32x32x16_bf16 v[16:31], v[188:191], v[144:147], v[16:31]
	ds_read_b64_tr_b16 v[188:189], v143 offset:0x3600
	ds_read_b64_tr_b16 v[190:191], v143 offset:0x3e00
	s_waitcnt lgkmcnt(6)
	v_mfma_f32_32x32x16_bf16 v[0:15], v[148:151], v[112:115], v[0:15]
	v_max_f32_e32 v112, v80, v81
	v_max3_f32 v112, v112, v82, v83
	v_max3_f32 v112, v112, v84, v85
	v_max3_f32 v112, v112, v86, v87
	v_max3_f32 v112, v112, v88, v89
	v_max3_f32 v112, v112, v90, v91
	v_max3_f32 v112, v112, v92, v93
	s_waitcnt lgkmcnt(4)
	v_mfma_f32_32x32x16_bf16 v[0:15], v[152:155], v[122:125], v[0:15]
	v_max3_f32 v112, v112, v94, v95
	v_max3_f32 v112, v112, v64, v65
	v_max3_f32 v112, v112, v66, v67
	v_max3_f32 v112, v112, v68, v69
	v_max3_f32 v112, v112, v70, v71
	v_max3_f32 v112, v112, v72, v73
	v_max3_f32 v112, v112, v74, v75
	v_max3_f32 v112, v112, v76, v77
	s_waitcnt lgkmcnt(2)
	v_mfma_f32_32x32x16_bf16 v[0:15], v[170:173], v[126:129], v[0:15]
	v_max3_f32 v112, v112, v78, v79
	v_mov_b32_e32 v113, v112
	s_nop 1
	v_permlane32_swap_b32_e32 v112, v113
	v_max_f32_e32 v112, v112, v113
	v_cmp_ge_f32_e32 vcc, s70, v112
	s_waitcnt lgkmcnt(0)
	v_mfma_f32_32x32x16_bf16 v[0:15], v[188:191], v[144:147], v[0:15]
	s_cmp_eq_u64 vcc, exec
	s_cselect_b64 s[4:5], -1, 0
	s_waitcnt vmcnt(0) lgkmcnt(0)
	s_barrier
	s_cbranch_scc1 .Lal_c_d2
	v_max_f32_e32 v242, 0, v112
	v_exp_f32_e64 v112, -v242
	s_nop 0
	v_pk_mul_f32 v[46:47], v[46:47], v[112:113] op_sel_hi:[1,0]
	v_pk_mul_f32 v[44:45], v[44:45], v[112:113] op_sel_hi:[1,0]
	v_pk_mul_f32 v[42:43], v[42:43], v[112:113] op_sel_hi:[1,0]
	v_pk_mul_f32 v[40:41], v[40:41], v[112:113] op_sel_hi:[1,0]
	v_pk_mul_f32 v[38:39], v[38:39], v[112:113] op_sel_hi:[1,0]
	v_pk_mul_f32 v[36:37], v[36:37], v[112:113] op_sel_hi:[1,0]
	v_pk_mul_f32 v[34:35], v[34:35], v[112:113] op_sel_hi:[1,0]
	v_pk_mul_f32 v[32:33], v[32:33], v[112:113] op_sel_hi:[1,0]
	v_pk_mul_f32 v[62:63], v[62:63], v[112:113] op_sel_hi:[1,0]
	v_pk_mul_f32 v[60:61], v[60:61], v[112:113] op_sel_hi:[1,0]
	v_pk_mul_f32 v[58:59], v[58:59], v[112:113] op_sel_hi:[1,0]
	v_pk_mul_f32 v[56:57], v[56:57], v[112:113] op_sel_hi:[1,0]
	v_pk_mul_f32 v[54:55], v[54:55], v[112:113] op_sel_hi:[1,0]
	v_pk_mul_f32 v[52:53], v[52:53], v[112:113] op_sel_hi:[1,0]
	v_pk_mul_f32 v[50:51], v[50:51], v[112:113] op_sel_hi:[1,0]
	v_pk_mul_f32 v[48:49], v[48:49], v[112:113] op_sel_hi:[1,0]
	v_pk_mul_f32 v[30:31], v[30:31], v[112:113] op_sel_hi:[1,0]
	v_pk_mul_f32 v[28:29], v[28:29], v[112:113] op_sel_hi:[1,0]
	v_pk_mul_f32 v[26:27], v[26:27], v[112:113] op_sel_hi:[1,0]
	v_pk_mul_f32 v[24:25], v[24:25], v[112:113] op_sel_hi:[1,0]
	v_pk_mul_f32 v[22:23], v[22:23], v[112:113] op_sel_hi:[1,0]
	v_pk_mul_f32 v[20:21], v[20:21], v[112:113] op_sel_hi:[1,0]
	v_pk_mul_f32 v[18:19], v[18:19], v[112:113] op_sel_hi:[1,0]
	v_pk_mul_f32 v[16:17], v[16:17], v[112:113] op_sel_hi:[1,0]
	v_pk_mul_f32 v[14:15], v[14:15], v[112:113] op_sel_hi:[1,0]
	v_pk_mul_f32 v[12:13], v[12:13], v[112:113] op_sel_hi:[1,0]
	v_pk_mul_f32 v[10:11], v[10:11], v[112:113] op_sel_hi:[1,0]
	v_pk_mul_f32 v[8:9], v[8:9], v[112:113] op_sel_hi:[1,0]
	v_pk_mul_f32 v[6:7], v[6:7], v[112:113] op_sel_hi:[1,0]
	v_pk_mul_f32 v[4:5], v[4:5], v[112:113] op_sel_hi:[1,0]
	v_pk_mul_f32 v[2:3], v[2:3], v[112:113] op_sel_hi:[1,0]
	v_pk_mul_f32 v[0:1], v[0:1], v[112:113] op_sel_hi:[1,0]
	v_sub_f32_e32 v80, v80, v242
	v_sub_f32_e32 v81, v81, v242
	v_sub_f32_e32 v82, v82, v242
	v_sub_f32_e32 v83, v83, v242
	v_sub_f32_e32 v84, v84, v242
	v_sub_f32_e32 v85, v85, v242
	v_sub_f32_e32 v86, v86, v242
	v_sub_f32_e32 v87, v87, v242
	v_sub_f32_e32 v88, v88, v242
	v_sub_f32_e32 v89, v89, v242
	v_sub_f32_e32 v90, v90, v242
	v_sub_f32_e32 v91, v91, v242
	v_sub_f32_e32 v92, v92, v242
	v_sub_f32_e32 v93, v93, v242
	v_sub_f32_e32 v94, v94, v242
	v_sub_f32_e32 v95, v95, v242
	v_sub_f32_e32 v64, v64, v242
	v_sub_f32_e32 v65, v65, v242
	v_sub_f32_e32 v66, v66, v242
	v_sub_f32_e32 v67, v67, v242
	v_sub_f32_e32 v68, v68, v242
	v_sub_f32_e32 v69, v69, v242
	v_sub_f32_e32 v70, v70, v242
	v_sub_f32_e32 v71, v71, v242
	v_sub_f32_e32 v72, v72, v242
	v_sub_f32_e32 v73, v73, v242
	v_sub_f32_e32 v74, v74, v242
	v_sub_f32_e32 v75, v75, v242
	v_sub_f32_e32 v76, v76, v242
	v_sub_f32_e32 v77, v77, v242
	v_sub_f32_e32 v78, v78, v242
	v_sub_f32_e32 v79, v79, v242
	v_sub_f32_e32 v226, v226, v242
	v_sub_f32_e32 v227, v227, v242
	v_sub_f32_e32 v228, v228, v242
	v_sub_f32_e32 v229, v229, v242
	v_sub_f32_e32 v230, v230, v242
	v_sub_f32_e32 v231, v231, v242
	v_sub_f32_e32 v232, v232, v242
	v_sub_f32_e32 v233, v233, v242
	v_sub_f32_e32 v234, v234, v242
	v_sub_f32_e32 v235, v235, v242
	v_sub_f32_e32 v236, v236, v242
	v_sub_f32_e32 v237, v237, v242
	v_sub_f32_e32 v238, v238, v242
	v_sub_f32_e32 v239, v239, v242
	v_sub_f32_e32 v240, v240, v242
	v_sub_f32_e32 v241, v241, v242
	s_branch .LBB0_133
